# GEMM main loops: A-fragment LDS read addresses kept in registers (no per-iteration adds), redundant post-barrier lgkmcnt waits dropped
# speedup vs baseline: 1.0141x; 1.0015x over previous
.LBB0_618:
	s_add_u32 s8, s12, s4
	s_addc_u32 s9, s13, s5
	s_lshl_b32 s23, s6, 5
	s_and_b32 s53, s23, 0x60
	s_add_i32 m0, s57, 0x18000
	v_lshl_add_u64 v[6:7], v[6:7], 0, s[54:55]
	s_lshl_b32 s22, s7, 13
	s_lshl_b32 s26, s53, 7
	s_waitcnt vmcnt(2)
	s_barrier
	global_load_lds_dwordx4 v[6:7], off
	v_lshl_add_u64 v[4:5], v[4:5], 0, s[54:55]
	s_add_i32 m0, s57, 0x1a000
	s_add_i32 s92, s57, 0x8000
	s_add_i32 s6, s57, 0xa000
	global_load_lds_dwordx4 v[4:5], off
	v_lshl_add_u64 v[2:3], v[2:3], 0, s[54:55]
	s_mov_b32 m0, s92
	s_add_u32 s4, s90, 0x80080
	global_load_lds_dwordx4 v[2:3], off
	v_lshl_add_u64 v[0:1], v[0:1], 0, s[54:55]
	s_mov_b32 m0, s6
	s_addc_u32 s5, s91, 0
	global_load_lds_dwordx4 v[0:1], off
	s_add_i32 m0, s57, 0x1c000
	v_lshl_add_u64 v[0:1], s[4:5], 0, v[130:131]
	global_load_lds_dwordx4 v[0:1], off
	v_lshl_add_u64 v[0:1], s[4:5], 0, v[134:135]
	s_add_i32 m0, s57, 0x1e000
	v_mov_b32_e32 v137, v209
	global_load_lds_dwordx4 v[0:1], off
	v_lshrrev_b32_e32 v1, 1, v8
	v_and_b32_e32 v1, 24, v1
	v_and_b32_e32 v0, 15, v8
	v_lshlrev_b32_e32 v2, 1, v1
	v_lshl_or_b32 v140, s7, 6, v0
	v_lshl_or_b32 v0, v0, 6, v2
	v_lshlrev_b32_e32 v2, 2, v8
	v_and_b32_e32 v2, 32, v2
	v_bitop3_b32 v3, v0, s22, v2 bitop3:0xde
	v_bitop3_b32 v141, v0, s26, v2 bitop3:0xde
	v_add_u32_e32 v222, 0x10000, v141
	v_add_u32_e32 v223, 0x14000, v141
	v_add_u32_e32 v224, 0x18000, v141
	v_add_u32_e32 v225, 0x1c000, v141
	v_lshlrev_b32_e32 v0, 15, v9
	v_and_b32_e32 v0, 0xffff0000, v0
	v_or_b32_e32 v142, s23, v1
	v_lshl_add_u32 v0, v10, 12, v0
	v_and_b32_e32 v1, 1, v9
	v_lshl_or_b32 v0, v1, 6, v0
	v_lshl_add_u32 v136, v11, 1, v0
	v_lshlrev_b32_e32 v0, 15, v12
	v_and_b32_e32 v0, 0xffff0000, v0
	s_waitcnt vmcnt(6)
	v_lshl_add_u32 v0, v13, 12, v0
	v_and_b32_e32 v1, 1, v12
	v_lshl_or_b32 v0, v1, 6, v0
	s_ashr_i32 s7, s95, 31
	v_lshl_add_u32 v138, v14, 1, v0
	v_mov_b32_e32 v139, v209
	s_mov_b32 s26, 0
	v_add_u32_e32 v143, 0, v3
	s_barrier
	s_branch .LBB0_621

.LBB0_631:
	s_add_u32 s22, s88, 0xfff80080
	s_addc_u32 s23, s89, -1
	s_add_i32 s44, 0, 0x10000
	s_cmp_eq_u32 s43, 28
	s_cselect_b32 s23, s30, s23
	s_cselect_b32 s22, s31, s22
	s_cselect_b32 s91, s38, s42
	s_cselect_b32 s90, s39, s41
	s_add_i32 s81, 0, 0x14000
	ds_read_b128 v[144:147], v222
	ds_read_b128 v[148:151], v222 offset:1024
	ds_read_b128 v[152:155], v222 offset:2048
	ds_read_b128 v[156:159], v222 offset:3072
	ds_read_b128 v[160:163], v223
	ds_read_b128 v[164:167], v223 offset:1024
	ds_read_b128 v[168:171], v223 offset:2048
	ds_read_b128 v[172:175], v223 offset:3072
	s_add_i32 m0, s57, 0xc000
	ds_read_b128 v[176:179], v143
	ds_read_b128 v[180:183], v143 offset:1024
	ds_read_b128 v[184:187], v143 offset:2048
	ds_read_b128 v[188:191], v143 offset:3072
	ds_read_b128 v[192:195], v143 offset:4096
	ds_read_b128 v[196:199], v143 offset:5120
	ds_read_b128 v[200:203], v143 offset:6144
	ds_read_b128 v[204:207], v143 offset:7168
	global_load_lds_dwordx4 v136, s[88:89]
	s_add_i32 m0, s57, 0xe000
	s_nop 0
	global_load_lds_dwordx4 v138, s[88:89]
	s_waitcnt vmcnt(8)
	s_waitcnt lgkmcnt(0)
	s_barrier
	v_mfma_f32_16x16x32_bf16 v[124:127], v[144:147], v[176:179], v[124:127]
	v_mfma_f32_16x16x32_bf16 v[120:123], v[152:155], v[176:179], v[120:123]
	v_mfma_f32_16x16x32_bf16 v[116:119], v[144:147], v[184:187], v[116:119]
	v_mfma_f32_16x16x32_bf16 v[112:115], v[152:155], v[184:187], v[112:115]
	v_mfma_f32_16x16x32_bf16 v[100:103], v[144:147], v[192:195], v[100:103]
	v_mfma_f32_16x16x32_bf16 v[96:99], v[152:155], v[192:195], v[96:99]
	v_mfma_f32_16x16x32_bf16 v[84:87], v[144:147], v[200:203], v[84:87]
	v_mfma_f32_16x16x32_bf16 v[80:83], v[152:155], v[200:203], v[80:83]
	v_mfma_f32_16x16x32_bf16 v[124:127], v[148:151], v[180:183], v[124:127]
	v_mfma_f32_16x16x32_bf16 v[120:123], v[156:159], v[180:183], v[120:123]
	v_mfma_f32_16x16x32_bf16 v[116:119], v[148:151], v[188:191], v[116:119]
	v_mfma_f32_16x16x32_bf16 v[112:115], v[156:159], v[188:191], v[112:115]
	v_mfma_f32_16x16x32_bf16 v[100:103], v[148:151], v[196:199], v[100:103]
	v_mfma_f32_16x16x32_bf16 v[96:99], v[156:159], v[196:199], v[96:99]
	v_mfma_f32_16x16x32_bf16 v[84:87], v[148:151], v[204:207], v[84:87]
	v_mfma_f32_16x16x32_bf16 v[80:83], v[156:159], v[204:207], v[80:83]
	v_mfma_f32_16x16x32_bf16 v[108:111], v[160:163], v[176:179], v[108:111]
	v_mfma_f32_16x16x32_bf16 v[104:107], v[168:171], v[176:179], v[104:107]
	v_mfma_f32_16x16x32_bf16 v[92:95], v[160:163], v[184:187], v[92:95]
	v_mfma_f32_16x16x32_bf16 v[88:91], v[168:171], v[184:187], v[88:91]
	v_mfma_f32_16x16x32_bf16 v[76:79], v[160:163], v[192:195], v[76:79]
	v_mfma_f32_16x16x32_bf16 v[72:75], v[168:171], v[192:195], v[72:75]
	v_mfma_f32_16x16x32_bf16 v[68:71], v[160:163], v[200:203], v[68:71]
	v_mfma_f32_16x16x32_bf16 v[64:67], v[168:171], v[200:203], v[64:67]
	v_mfma_f32_16x16x32_bf16 v[108:111], v[164:167], v[180:183], v[108:111]
	v_mfma_f32_16x16x32_bf16 v[104:107], v[172:175], v[180:183], v[104:107]
	v_mfma_f32_16x16x32_bf16 v[92:95], v[164:167], v[188:191], v[92:95]
	v_mfma_f32_16x16x32_bf16 v[88:91], v[172:175], v[188:191], v[88:91]
	v_mfma_f32_16x16x32_bf16 v[76:79], v[164:167], v[196:199], v[76:79]
	v_mfma_f32_16x16x32_bf16 v[72:75], v[172:175], v[196:199], v[72:75]
	v_mfma_f32_16x16x32_bf16 v[68:71], v[164:167], v[204:207], v[68:71]
	v_mfma_f32_16x16x32_bf16 v[64:67], v[172:175], v[204:207], v[64:67]
	s_barrier
	s_add_i32 s44, s44, s96
	s_mov_b32 m0, s44
	ds_read_b128 v[176:179], v143 offset:16384
	ds_read_b128 v[180:183], v143 offset:17408
	ds_read_b128 v[184:187], v143 offset:18432
	ds_read_b128 v[188:191], v143 offset:19456
	ds_read_b128 v[192:195], v143 offset:20480
	ds_read_b128 v[196:199], v143 offset:21504
	ds_read_b128 v[200:203], v143 offset:22528
	ds_read_b128 v[204:207], v143 offset:23552
	global_load_lds_dwordx4 v130, s[90:91]
	s_add_i32 m0, s44, 0x2000
	s_add_u32 s44, s90, 0x80000
	s_addc_u32 s45, s91, 0
	s_add_i32 s81, s81, s96
	global_load_lds_dwordx4 v134, s[90:91]
	s_mov_b32 m0, s81
	s_nop 0
	global_load_lds_dwordx4 v130, s[44:45]
	s_add_i32 m0, s81, 0x2000
	s_nop 0
	global_load_lds_dwordx4 v134, s[44:45]
	s_mov_b32 m0, s57
	s_nop 0
	global_load_lds_dwordx4 v128, s[22:23]
	s_mov_b32 m0, s97
	s_nop 0
	global_load_lds_dwordx4 v132, s[22:23]
	s_waitcnt vmcnt(8)
	s_waitcnt lgkmcnt(0)
	s_barrier
	v_mfma_f32_16x16x32_bf16 v[60:63], v[144:147], v[176:179], v[60:63]
	v_mfma_f32_16x16x32_bf16 v[56:59], v[152:155], v[176:179], v[56:59]
	v_mfma_f32_16x16x32_bf16 v[52:55], v[144:147], v[184:187], v[52:55]
	v_mfma_f32_16x16x32_bf16 v[48:51], v[152:155], v[184:187], v[48:51]
	v_mfma_f32_16x16x32_bf16 v[36:39], v[144:147], v[192:195], v[36:39]
	v_mfma_f32_16x16x32_bf16 v[32:35], v[152:155], v[192:195], v[32:35]
	v_mfma_f32_16x16x32_bf16 v[20:23], v[144:147], v[200:203], v[20:23]
	v_mfma_f32_16x16x32_bf16 v[16:19], v[152:155], v[200:203], v[16:19]
	v_mfma_f32_16x16x32_bf16 v[60:63], v[148:151], v[180:183], v[60:63]
	v_mfma_f32_16x16x32_bf16 v[56:59], v[156:159], v[180:183], v[56:59]
	v_mfma_f32_16x16x32_bf16 v[52:55], v[148:151], v[188:191], v[52:55]
	v_mfma_f32_16x16x32_bf16 v[48:51], v[156:159], v[188:191], v[48:51]
	v_mfma_f32_16x16x32_bf16 v[36:39], v[148:151], v[196:199], v[36:39]
	v_mfma_f32_16x16x32_bf16 v[32:35], v[156:159], v[196:199], v[32:35]
	v_mfma_f32_16x16x32_bf16 v[20:23], v[148:151], v[204:207], v[20:23]
	v_mfma_f32_16x16x32_bf16 v[16:19], v[156:159], v[204:207], v[16:19]
	v_mfma_f32_16x16x32_bf16 v[44:47], v[160:163], v[176:179], v[44:47]
	v_mfma_f32_16x16x32_bf16 v[40:43], v[168:171], v[176:179], v[40:43]
	v_mfma_f32_16x16x32_bf16 v[28:31], v[160:163], v[184:187], v[28:31]
	v_mfma_f32_16x16x32_bf16 v[24:27], v[168:171], v[184:187], v[24:27]
	v_mfma_f32_16x16x32_bf16 v[12:15], v[160:163], v[192:195], v[12:15]
	v_mfma_f32_16x16x32_bf16 v[8:11], v[168:171], v[192:195], v[8:11]
	v_mfma_f32_16x16x32_bf16 v[4:7], v[160:163], v[200:203], v[4:7]
	v_mfma_f32_16x16x32_bf16 v[0:3], v[168:171], v[200:203], v[0:3]
	v_mfma_f32_16x16x32_bf16 v[44:47], v[164:167], v[180:183], v[44:47]
	v_mfma_f32_16x16x32_bf16 v[40:43], v[172:175], v[180:183], v[40:43]
	v_mfma_f32_16x16x32_bf16 v[28:31], v[164:167], v[188:191], v[28:31]
	v_mfma_f32_16x16x32_bf16 v[24:27], v[172:175], v[188:191], v[24:27]
	v_mfma_f32_16x16x32_bf16 v[12:15], v[164:167], v[196:199], v[12:15]
	v_mfma_f32_16x16x32_bf16 v[8:11], v[172:175], v[196:199], v[8:11]
	v_mfma_f32_16x16x32_bf16 v[4:7], v[164:167], v[204:207], v[4:7]
	v_mfma_f32_16x16x32_bf16 v[0:3], v[172:175], v[204:207], v[0:3]
	s_barrier
	s_add_i32 s44, 0, 0x18000
	s_add_i32 s45, 0, 0x1c000
	ds_read_b128 v[144:147], v224
	ds_read_b128 v[148:151], v224 offset:1024
	ds_read_b128 v[152:155], v224 offset:2048
	ds_read_b128 v[156:159], v224 offset:3072
	ds_read_b128 v[160:163], v225
	ds_read_b128 v[164:167], v225 offset:1024
	ds_read_b128 v[168:171], v225 offset:2048
	ds_read_b128 v[172:175], v225 offset:3072
	s_add_u32 s22, s22, 0x80000
	s_addc_u32 s23, s23, 0
	s_mov_b32 m0, s93
	ds_read_b128 v[176:179], v143 offset:32768
	ds_read_b128 v[180:183], v143 offset:33792
	ds_read_b128 v[184:187], v143 offset:34816
	ds_read_b128 v[188:191], v143 offset:35840
	ds_read_b128 v[192:195], v143 offset:36864
	ds_read_b128 v[196:199], v143 offset:37888
	ds_read_b128 v[200:203], v143 offset:38912
	ds_read_b128 v[204:207], v143 offset:39936
	global_load_lds_dwordx4 v128, s[22:23]
	s_mov_b32 m0, s94
	s_nop 0
	global_load_lds_dwordx4 v132, s[22:23]
	s_waitcnt vmcnt(8)
	s_waitcnt lgkmcnt(0)
	s_barrier
	v_mfma_f32_16x16x32_bf16 v[124:127], v[144:147], v[176:179], v[124:127]
	v_mfma_f32_16x16x32_bf16 v[120:123], v[152:155], v[176:179], v[120:123]
	v_mfma_f32_16x16x32_bf16 v[116:119], v[144:147], v[184:187], v[116:119]
	v_mfma_f32_16x16x32_bf16 v[112:115], v[152:155], v[184:187], v[112:115]
	v_mfma_f32_16x16x32_bf16 v[100:103], v[144:147], v[192:195], v[100:103]
	v_mfma_f32_16x16x32_bf16 v[96:99], v[152:155], v[192:195], v[96:99]
	v_mfma_f32_16x16x32_bf16 v[84:87], v[144:147], v[200:203], v[84:87]
	v_mfma_f32_16x16x32_bf16 v[80:83], v[152:155], v[200:203], v[80:83]
	v_mfma_f32_16x16x32_bf16 v[124:127], v[148:151], v[180:183], v[124:127]
	v_mfma_f32_16x16x32_bf16 v[120:123], v[156:159], v[180:183], v[120:123]
	v_mfma_f32_16x16x32_bf16 v[116:119], v[148:151], v[188:191], v[116:119]
	v_mfma_f32_16x16x32_bf16 v[112:115], v[156:159], v[188:191], v[112:115]
	v_mfma_f32_16x16x32_bf16 v[100:103], v[148:151], v[196:199], v[100:103]
	v_mfma_f32_16x16x32_bf16 v[96:99], v[156:159], v[196:199], v[96:99]
	v_mfma_f32_16x16x32_bf16 v[84:87], v[148:151], v[204:207], v[84:87]
	v_mfma_f32_16x16x32_bf16 v[80:83], v[156:159], v[204:207], v[80:83]
	v_mfma_f32_16x16x32_bf16 v[108:111], v[160:163], v[176:179], v[108:111]
	v_mfma_f32_16x16x32_bf16 v[104:107], v[168:171], v[176:179], v[104:107]
	v_mfma_f32_16x16x32_bf16 v[92:95], v[160:163], v[184:187], v[92:95]
	v_mfma_f32_16x16x32_bf16 v[88:91], v[168:171], v[184:187], v[88:91]
	v_mfma_f32_16x16x32_bf16 v[76:79], v[160:163], v[192:195], v[76:79]
	v_mfma_f32_16x16x32_bf16 v[72:75], v[168:171], v[192:195], v[72:75]
	v_mfma_f32_16x16x32_bf16 v[68:71], v[160:163], v[200:203], v[68:71]
	v_mfma_f32_16x16x32_bf16 v[64:67], v[168:171], v[200:203], v[64:67]
	v_mfma_f32_16x16x32_bf16 v[108:111], v[164:167], v[180:183], v[108:111]
	v_mfma_f32_16x16x32_bf16 v[104:107], v[172:175], v[180:183], v[104:107]
	v_mfma_f32_16x16x32_bf16 v[92:95], v[164:167], v[188:191], v[92:95]
	v_mfma_f32_16x16x32_bf16 v[88:91], v[172:175], v[188:191], v[88:91]
	v_mfma_f32_16x16x32_bf16 v[76:79], v[164:167], v[196:199], v[76:79]
	v_mfma_f32_16x16x32_bf16 v[72:75], v[172:175], v[196:199], v[72:75]
	v_mfma_f32_16x16x32_bf16 v[68:71], v[164:167], v[204:207], v[68:71]
	v_mfma_f32_16x16x32_bf16 v[64:67], v[172:175], v[204:207], v[64:67]
	s_barrier
	s_add_i32 s22, s44, s96
	s_add_i32 m0, s22, 0xffffff80
	ds_read_b128 v[176:179], v143 offset:49152
	ds_read_b128 v[180:183], v143 offset:50176
	ds_read_b128 v[184:187], v143 offset:51200
	ds_read_b128 v[188:191], v143 offset:52224
	ds_read_b128 v[192:195], v143 offset:53248
	ds_read_b128 v[196:199], v143 offset:54272
	ds_read_b128 v[200:203], v143 offset:55296
	ds_read_b128 v[204:207], v143 offset:56320
	global_load_lds_dwordx4 v130, s[90:91] offset:128
	s_add_i32 m0, s22, 0x1f80
	s_add_u32 s22, s90, 0x80080
	s_addc_u32 s23, s91, 0
	s_add_i32 s44, s45, s96
	global_load_lds_dwordx4 v134, s[90:91] offset:128
	s_mov_b32 m0, s44
	s_nop 0
	global_load_lds_dwordx4 v130, s[22:23]
	s_add_i32 m0, s44, 0x2000
	s_nop 0
	global_load_lds_dwordx4 v134, s[22:23]
	s_add_u32 s22, s88, 0xfff80080
	s_addc_u32 s23, s89, -1
	s_cmp_eq_u32 s43, 28
	s_cselect_b32 s23, s30, s23
	s_cselect_b32 s22, s31, s22
	s_add_i32 m0, s92, 0xffffff80
	s_nop 0
	global_load_lds_dwordx4 v128, s[22:23] offset:128
	s_add_i32 m0, s6, 0xffffff80
	s_nop 0
	global_load_lds_dwordx4 v132, s[22:23] offset:128
	s_waitcnt vmcnt(8)
	s_waitcnt lgkmcnt(0)
	s_barrier
	v_mfma_f32_16x16x32_bf16 v[60:63], v[144:147], v[176:179], v[60:63]
	v_mfma_f32_16x16x32_bf16 v[56:59], v[152:155], v[176:179], v[56:59]
	v_mfma_f32_16x16x32_bf16 v[52:55], v[144:147], v[184:187], v[52:55]
	v_mfma_f32_16x16x32_bf16 v[48:51], v[152:155], v[184:187], v[48:51]
	v_mfma_f32_16x16x32_bf16 v[36:39], v[144:147], v[192:195], v[36:39]
	v_mfma_f32_16x16x32_bf16 v[32:35], v[152:155], v[192:195], v[32:35]
	v_mfma_f32_16x16x32_bf16 v[20:23], v[144:147], v[200:203], v[20:23]
	v_mfma_f32_16x16x32_bf16 v[16:19], v[152:155], v[200:203], v[16:19]
	v_mfma_f32_16x16x32_bf16 v[60:63], v[148:151], v[180:183], v[60:63]
	v_mfma_f32_16x16x32_bf16 v[56:59], v[156:159], v[180:183], v[56:59]
	v_mfma_f32_16x16x32_bf16 v[52:55], v[148:151], v[188:191], v[52:55]
	v_mfma_f32_16x16x32_bf16 v[48:51], v[156:159], v[188:191], v[48:51]
	v_mfma_f32_16x16x32_bf16 v[36:39], v[148:151], v[196:199], v[36:39]
	v_mfma_f32_16x16x32_bf16 v[32:35], v[156:159], v[196:199], v[32:35]
	v_mfma_f32_16x16x32_bf16 v[20:23], v[148:151], v[204:207], v[20:23]
	v_mfma_f32_16x16x32_bf16 v[16:19], v[156:159], v[204:207], v[16:19]
	v_mfma_f32_16x16x32_bf16 v[44:47], v[160:163], v[176:179], v[44:47]
	v_mfma_f32_16x16x32_bf16 v[40:43], v[168:171], v[176:179], v[40:43]
	v_mfma_f32_16x16x32_bf16 v[28:31], v[160:163], v[184:187], v[28:31]
	v_mfma_f32_16x16x32_bf16 v[24:27], v[168:171], v[184:187], v[24:27]
	v_mfma_f32_16x16x32_bf16 v[12:15], v[160:163], v[192:195], v[12:15]
	v_mfma_f32_16x16x32_bf16 v[8:11], v[168:171], v[192:195], v[8:11]
	v_mfma_f32_16x16x32_bf16 v[4:7], v[160:163], v[200:203], v[4:7]
	v_mfma_f32_16x16x32_bf16 v[0:3], v[168:171], v[200:203], v[0:3]
	v_mfma_f32_16x16x32_bf16 v[44:47], v[164:167], v[180:183], v[44:47]
	v_mfma_f32_16x16x32_bf16 v[40:43], v[172:175], v[180:183], v[40:43]
	v_mfma_f32_16x16x32_bf16 v[28:31], v[164:167], v[188:191], v[28:31]
	v_mfma_f32_16x16x32_bf16 v[24:27], v[172:175], v[188:191], v[24:27]
	v_mfma_f32_16x16x32_bf16 v[12:15], v[164:167], v[196:199], v[12:15]
	v_mfma_f32_16x16x32_bf16 v[8:11], v[172:175], v[196:199], v[8:11]
	v_mfma_f32_16x16x32_bf16 v[4:7], v[164:167], v[204:207], v[4:7]
	v_mfma_f32_16x16x32_bf16 v[0:3], v[172:175], v[204:207], v[0:3]
	s_barrier
	s_add_i32 s43, s43, 2
	s_add_u32 s88, s88, 0x100
	s_addc_u32 s89, s89, 0
	s_add_u32 s41, s41, 0x100
	s_addc_u32 s42, s42, 0
	s_cmp_gt_u32 s43, 29
	s_cbranch_scc0 .LBB0_631
	s_cmp_eq_u32 s40, 0
	s_cselect_b64 s[30:31], -1, 0
	s_cmp_lg_u32 s40, 0
	s_mov_b64 s[38:39], -1
	s_cbranch_scc0 .LBB0_634
	s_lshl_b32 s22, s80, 8
	s_or_b32 s22, s22, s53
	s_ashr_i32 s22, s22, 6
	s_mov_b64 s[38:39], 0

.LBB0_1249:
	v_lshl_add_u64 v[6:7], s[96:97], 0, v[208:209]
	v_mov_b32_e32 v129, v209
	v_lshl_add_u64 v[8:9], s[96:97], 0, v[128:129]
	s_and_b32 s4, s7, 3
	s_add_i32 m0, s45, 0x18000
	v_lshl_add_u64 v[6:7], v[6:7], 0, s[54:55]
	v_lshl_add_u64 v[10:11], s[92:93], 0, v[208:209]
	s_lshl_b32 s47, s31, 6
	s_lshl_b32 s7, s31, 13
	s_lshl_b32 s8, s4, 12
	s_waitcnt vmcnt(2)
	s_barrier
	global_load_lds_dwordx4 v[6:7], off
	v_lshl_add_u64 v[6:7], v[8:9], 0, s[54:55]
	s_add_i32 m0, s45, 0x1a000
	s_add_i32 s9, s45, 0x8000
	s_add_i32 s12, s45, 0xa000
	v_lshl_add_u64 v[12:13], s[92:93], 0, v[128:129]
	s_mov_b32 s46, s4
	global_load_lds_dwordx4 v[6:7], off
	v_lshl_add_u64 v[6:7], v[10:11], 0, s[54:55]
	s_mov_b32 m0, s9
	s_add_u32 s4, s96, 0x80080
	global_load_lds_dwordx4 v[6:7], off
	v_lshl_add_u64 v[6:7], v[12:13], 0, s[54:55]
	s_mov_b32 m0, s12
	s_addc_u32 s5, s97, 0
	global_load_lds_dwordx4 v[6:7], off
	s_add_i32 m0, s45, 0x1c000
	v_lshl_add_u64 v[6:7], s[4:5], 0, v[208:209]
	global_load_lds_dwordx4 v[6:7], off
	v_lshl_add_u64 v[6:7], s[4:5], 0, v[128:129]
	s_add_i32 m0, s45, 0x1e000
	v_and_b32_e32 v214, 15, v246
	global_load_lds_dwordx4 v[6:7], off
	v_bfe_u32 v215, v246, 4, 2
	v_lshlrev_b32_e32 v6, 4, v215
	v_lshlrev_b32_e32 v7, 2, v214
	v_lshl_or_b32 v6, v214, 6, v6
	v_and_b32_e32 v8, 32, v7
	v_bitop3_b32 v9, v6, s7, v8 bitop3:0xde
	v_bitop3_b32 v138, v6, s8, v8 bitop3:0xde
	v_add_u32_e32 v222, 0x10000, v138
	v_add_u32_e32 v223, 0x14000, v138
	v_add_u32_e32 v224, 0x18000, v138
	v_add_u32_e32 v225, 0x1c000, v138
	v_lshlrev_b32_e32 v6, 15, v3
	v_and_b32_e32 v6, 0xffff0000, v6
	v_lshl_add_u32 v4, v4, 12, v6
	v_and_b32_e32 v3, 1, v3
	v_lshl_or_b32 v3, v3, 6, v4
	v_lshl_add_u32 v4, v5, 1, v3
	v_lshlrev_b32_e32 v3, 15, v0
	s_and_b32 s4, s6, 0xffffff00
	v_and_b32_e32 v3, 0xffff0000, v3
	s_cmpk_lt_u32 s6, 0x100
	v_lshl_add_u32 v1, v1, 12, v3
	v_and_b32_e32 v0, 1, v0
	s_cselect_b64 s[86:87], -1, 0
	s_add_i32 s4, s4, 0
	v_lshl_or_b32 v0, v0, 6, v1
	v_add_u32_e32 v139, s4, v7
	v_mov_b32_e32 v5, v209
	s_mov_b64 s[4:5], 0x80080
	v_lshl_add_u32 v0, v2, 1, v0
	v_mov_b32_e32 v1, v209
	s_waitcnt vmcnt(6)
	v_lshl_add_u64 v[130:131], v[4:5], 0, s[4:5]
	v_lshl_add_u64 v[132:133], v[0:1], 0, s[4:5]
	v_mov_b32_e32 v2, v209
	v_mov_b32_e32 v3, v209
	v_readlane_b32 s4, v254, 26
	v_mov_b32_e32 v0, v209
	v_add_u32_e32 v140, 0, v9
	v_mov_b64_e32 v[6:7], v[2:3]
	v_mov_b64_e32 v[18:19], v[2:3]
	v_mov_b64_e32 v[22:23], v[2:3]
	v_mov_b64_e32 v[34:35], v[2:3]
	v_mov_b64_e32 v[38:39], v[2:3]
	v_mov_b64_e32 v[50:51], v[2:3]
	v_mov_b64_e32 v[54:55], v[2:3]
	v_mov_b64_e32 v[10:11], v[2:3]
	v_mov_b64_e32 v[14:15], v[2:3]
	v_mov_b64_e32 v[26:27], v[2:3]
	v_mov_b64_e32 v[30:31], v[2:3]
	v_mov_b64_e32 v[42:43], v[2:3]
	v_mov_b64_e32 v[46:47], v[2:3]
	v_mov_b64_e32 v[58:59], v[2:3]
	v_mov_b64_e32 v[62:63], v[2:3]
	v_mov_b64_e32 v[66:67], v[2:3]
	v_mov_b64_e32 v[70:71], v[2:3]
	v_mov_b64_e32 v[82:83], v[2:3]
	v_mov_b64_e32 v[86:87], v[2:3]
	v_mov_b64_e32 v[98:99], v[2:3]
	v_mov_b64_e32 v[102:103], v[2:3]
	v_mov_b64_e32 v[114:115], v[2:3]
	v_mov_b64_e32 v[118:119], v[2:3]
	v_mov_b64_e32 v[74:75], v[2:3]
	v_mov_b64_e32 v[78:79], v[2:3]
	v_mov_b64_e32 v[90:91], v[2:3]
	v_mov_b64_e32 v[94:95], v[2:3]
	v_mov_b64_e32 v[106:107], v[2:3]
	v_mov_b64_e32 v[110:111], v[2:3]
	v_mov_b64_e32 v[122:123], v[2:3]
	v_mov_b64_e32 v[126:127], v[2:3]
	s_mov_b32 s84, s4
	v_readlane_b32 s4, v254, 27
	v_or_b32_e32 v247, s47, v214
	s_mov_b32 s14, 0
	v_mov_b64_e32 v[4:5], v[0:1]
	v_mov_b64_e32 v[16:17], v[0:1]
	v_mov_b64_e32 v[20:21], v[0:1]
	v_mov_b64_e32 v[32:33], v[0:1]
	v_mov_b64_e32 v[36:37], v[0:1]
	v_mov_b64_e32 v[48:49], v[0:1]
	v_mov_b64_e32 v[52:53], v[0:1]
	v_mov_b64_e32 v[8:9], v[0:1]
	v_mov_b64_e32 v[12:13], v[0:1]
	v_mov_b64_e32 v[24:25], v[0:1]
	v_mov_b64_e32 v[28:29], v[0:1]
	v_mov_b64_e32 v[40:41], v[0:1]
	v_mov_b64_e32 v[44:45], v[0:1]
	v_mov_b64_e32 v[56:57], v[0:1]
	v_mov_b64_e32 v[60:61], v[0:1]
	v_mov_b64_e32 v[64:65], v[0:1]
	v_mov_b64_e32 v[68:69], v[0:1]
	v_mov_b64_e32 v[80:81], v[0:1]
	v_mov_b64_e32 v[84:85], v[0:1]
	v_mov_b64_e32 v[96:97], v[0:1]
	v_mov_b64_e32 v[100:101], v[0:1]
	v_mov_b64_e32 v[112:113], v[0:1]
	v_mov_b64_e32 v[116:117], v[0:1]
	v_mov_b64_e32 v[72:73], v[0:1]
	v_mov_b64_e32 v[76:77], v[0:1]
	v_mov_b64_e32 v[88:89], v[0:1]
	v_mov_b64_e32 v[92:93], v[0:1]
	v_mov_b64_e32 v[104:105], v[0:1]
	v_mov_b64_e32 v[108:109], v[0:1]
	v_mov_b64_e32 v[120:121], v[0:1]
	v_mov_b64_e32 v[124:125], v[0:1]
	s_mov_b32 s26, s4
	s_barrier
	v_readlane_b32 s5, v254, 28

.LBB0_1259:
	s_add_u32 s22, s92, s76
	s_addc_u32 s23, s93, s77
	s_add_u32 s80, s96, s76
	s_addc_u32 s81, s97, s77
	s_cmp_eq_u32 s44, 0
	s_cselect_b32 s23, s15, s23
	s_cselect_b32 s22, s91, s22
	s_cselect_b32 vcc_hi, s89, s81
	s_cselect_b32 vcc_lo, s8, s80
	s_add_i32 s80, 0, 0x10000
	s_add_i32 s83, 0, 0x14000
	ds_read_b128 v[142:145], v222
	ds_read_b128 v[146:149], v222 offset:1024
	ds_read_b128 v[150:153], v222 offset:2048
	ds_read_b128 v[154:157], v222 offset:3072
	ds_read_b128 v[158:161], v223
	ds_read_b128 v[162:165], v223 offset:1024
	ds_read_b128 v[166:169], v223 offset:2048
	ds_read_b128 v[170:173], v223 offset:3072
	s_add_i32 m0, s45, 0xc000
	ds_read_b128 v[174:177], v140
	ds_read_b128 v[178:181], v140 offset:1024
	ds_read_b128 v[182:185], v140 offset:2048
	ds_read_b128 v[186:189], v140 offset:3072
	ds_read_b128 v[190:193], v140 offset:4096
	ds_read_b128 v[194:197], v140 offset:5120
	ds_read_b128 v[198:201], v140 offset:6144
	ds_read_b128 v[202:205], v140 offset:7168
	global_load_lds_dwordx4 v136, s[92:93]
	s_add_i32 m0, s45, 0xe000
	s_nop 0
	global_load_lds_dwordx4 v134, s[92:93]
	s_waitcnt vmcnt(8)
	s_waitcnt lgkmcnt(0)
	s_barrier
	v_mfma_f32_16x16x32_bf16 v[124:127], v[142:145], v[174:177], v[124:127]
	v_mfma_f32_16x16x32_bf16 v[120:123], v[150:153], v[174:177], v[120:123]
	v_mfma_f32_16x16x32_bf16 v[108:111], v[142:145], v[182:185], v[108:111]
	v_mfma_f32_16x16x32_bf16 v[104:107], v[150:153], v[182:185], v[104:107]
	v_mfma_f32_16x16x32_bf16 v[92:95], v[142:145], v[190:193], v[92:95]
	v_mfma_f32_16x16x32_bf16 v[88:91], v[150:153], v[190:193], v[88:91]
	v_mfma_f32_16x16x32_bf16 v[76:79], v[142:145], v[198:201], v[76:79]
	v_mfma_f32_16x16x32_bf16 v[72:75], v[150:153], v[198:201], v[72:75]
	v_mfma_f32_16x16x32_bf16 v[124:127], v[146:149], v[178:181], v[124:127]
	v_mfma_f32_16x16x32_bf16 v[120:123], v[154:157], v[178:181], v[120:123]
	v_mfma_f32_16x16x32_bf16 v[108:111], v[146:149], v[186:189], v[108:111]
	v_mfma_f32_16x16x32_bf16 v[104:107], v[154:157], v[186:189], v[104:107]
	v_mfma_f32_16x16x32_bf16 v[92:95], v[146:149], v[194:197], v[92:95]
	v_mfma_f32_16x16x32_bf16 v[88:91], v[154:157], v[194:197], v[88:91]
	v_mfma_f32_16x16x32_bf16 v[76:79], v[146:149], v[202:205], v[76:79]
	v_mfma_f32_16x16x32_bf16 v[72:75], v[154:157], v[202:205], v[72:75]
	v_mfma_f32_16x16x32_bf16 v[116:119], v[158:161], v[174:177], v[116:119]
	v_mfma_f32_16x16x32_bf16 v[112:115], v[166:169], v[174:177], v[112:115]
	v_mfma_f32_16x16x32_bf16 v[100:103], v[158:161], v[182:185], v[100:103]
	v_mfma_f32_16x16x32_bf16 v[96:99], v[166:169], v[182:185], v[96:99]
	v_mfma_f32_16x16x32_bf16 v[84:87], v[158:161], v[190:193], v[84:87]
	v_mfma_f32_16x16x32_bf16 v[80:83], v[166:169], v[190:193], v[80:83]
	v_mfma_f32_16x16x32_bf16 v[68:71], v[158:161], v[198:201], v[68:71]
	v_mfma_f32_16x16x32_bf16 v[64:67], v[166:169], v[198:201], v[64:67]
	v_mfma_f32_16x16x32_bf16 v[116:119], v[162:165], v[178:181], v[116:119]
	v_mfma_f32_16x16x32_bf16 v[112:115], v[170:173], v[178:181], v[112:115]
	v_mfma_f32_16x16x32_bf16 v[100:103], v[162:165], v[186:189], v[100:103]
	v_mfma_f32_16x16x32_bf16 v[96:99], v[170:173], v[186:189], v[96:99]
	v_mfma_f32_16x16x32_bf16 v[84:87], v[162:165], v[194:197], v[84:87]
	v_mfma_f32_16x16x32_bf16 v[80:83], v[170:173], v[194:197], v[80:83]
	v_mfma_f32_16x16x32_bf16 v[68:71], v[162:165], v[202:205], v[68:71]
	v_mfma_f32_16x16x32_bf16 v[64:67], v[170:173], v[202:205], v[64:67]
	s_barrier
	s_add_i32 s80, s80, s43
	s_mov_b32 m0, s80
	ds_read_b128 v[174:177], v140 offset:16384
	ds_read_b128 v[178:181], v140 offset:17408
	ds_read_b128 v[182:185], v140 offset:18432
	ds_read_b128 v[186:189], v140 offset:19456
	ds_read_b128 v[190:193], v140 offset:20480
	ds_read_b128 v[194:197], v140 offset:21504
	ds_read_b128 v[198:201], v140 offset:22528
	ds_read_b128 v[202:205], v140 offset:23552
	global_load_lds_dwordx4 v208, vcc
	s_add_i32 m0, s80, 0x2000
	s_add_u32 s80, vcc_lo, 0x80000
	s_addc_u32 s81, vcc_hi, 0
	s_add_i32 s83, s83, s43
	global_load_lds_dwordx4 v128, vcc
	s_mov_b32 m0, s83
	s_nop 0
	global_load_lds_dwordx4 v208, s[80:81]
	s_add_i32 m0, s83, 0x2000
	s_nop 0
	global_load_lds_dwordx4 v128, s[80:81]
	s_mov_b32 m0, s45
	s_nop 0
	global_load_lds_dwordx4 v208, s[22:23]
	s_mov_b32 m0, s52
	s_nop 0
	global_load_lds_dwordx4 v128, s[22:23]
	s_waitcnt vmcnt(8)
	s_waitcnt lgkmcnt(0)
	s_barrier
	v_mfma_f32_16x16x32_bf16 v[60:63], v[142:145], v[174:177], v[60:63]
	v_mfma_f32_16x16x32_bf16 v[56:59], v[150:153], v[174:177], v[56:59]
	v_mfma_f32_16x16x32_bf16 v[44:47], v[142:145], v[182:185], v[44:47]
	v_mfma_f32_16x16x32_bf16 v[40:43], v[150:153], v[182:185], v[40:43]
	v_mfma_f32_16x16x32_bf16 v[28:31], v[142:145], v[190:193], v[28:31]
	v_mfma_f32_16x16x32_bf16 v[24:27], v[150:153], v[190:193], v[24:27]
	v_mfma_f32_16x16x32_bf16 v[12:15], v[142:145], v[198:201], v[12:15]
	v_mfma_f32_16x16x32_bf16 v[8:11], v[150:153], v[198:201], v[8:11]
	v_mfma_f32_16x16x32_bf16 v[60:63], v[146:149], v[178:181], v[60:63]
	v_mfma_f32_16x16x32_bf16 v[56:59], v[154:157], v[178:181], v[56:59]
	v_mfma_f32_16x16x32_bf16 v[44:47], v[146:149], v[186:189], v[44:47]
	v_mfma_f32_16x16x32_bf16 v[40:43], v[154:157], v[186:189], v[40:43]
	v_mfma_f32_16x16x32_bf16 v[28:31], v[146:149], v[194:197], v[28:31]
	v_mfma_f32_16x16x32_bf16 v[24:27], v[154:157], v[194:197], v[24:27]
	v_mfma_f32_16x16x32_bf16 v[12:15], v[146:149], v[202:205], v[12:15]
	v_mfma_f32_16x16x32_bf16 v[8:11], v[154:157], v[202:205], v[8:11]
	v_mfma_f32_16x16x32_bf16 v[52:55], v[158:161], v[174:177], v[52:55]
	v_mfma_f32_16x16x32_bf16 v[48:51], v[166:169], v[174:177], v[48:51]
	v_mfma_f32_16x16x32_bf16 v[36:39], v[158:161], v[182:185], v[36:39]
	v_mfma_f32_16x16x32_bf16 v[32:35], v[166:169], v[182:185], v[32:35]
	v_mfma_f32_16x16x32_bf16 v[20:23], v[158:161], v[190:193], v[20:23]
	v_mfma_f32_16x16x32_bf16 v[16:19], v[166:169], v[190:193], v[16:19]
	v_mfma_f32_16x16x32_bf16 v[4:7], v[158:161], v[198:201], v[4:7]
	v_mfma_f32_16x16x32_bf16 v[0:3], v[166:169], v[198:201], v[0:3]
	v_mfma_f32_16x16x32_bf16 v[52:55], v[162:165], v[178:181], v[52:55]
	v_mfma_f32_16x16x32_bf16 v[48:51], v[170:173], v[178:181], v[48:51]
	v_mfma_f32_16x16x32_bf16 v[36:39], v[162:165], v[186:189], v[36:39]
	v_mfma_f32_16x16x32_bf16 v[32:35], v[170:173], v[186:189], v[32:35]
	v_mfma_f32_16x16x32_bf16 v[20:23], v[162:165], v[194:197], v[20:23]
	v_mfma_f32_16x16x32_bf16 v[16:19], v[170:173], v[194:197], v[16:19]
	v_mfma_f32_16x16x32_bf16 v[4:7], v[162:165], v[202:205], v[4:7]
	v_mfma_f32_16x16x32_bf16 v[0:3], v[170:173], v[202:205], v[0:3]
	s_barrier
	s_add_i32 s80, 0, 0x18000
	s_add_i32 s81, 0, 0x1c000
	ds_read_b128 v[142:145], v224
	ds_read_b128 v[146:149], v224 offset:1024
	ds_read_b128 v[150:153], v224 offset:2048
	ds_read_b128 v[154:157], v224 offset:3072
	ds_read_b128 v[158:161], v225
	ds_read_b128 v[162:165], v225 offset:1024
	ds_read_b128 v[166:169], v225 offset:2048
	ds_read_b128 v[170:173], v225 offset:3072
	s_add_u32 s22, s22, 0x80000
	s_addc_u32 s23, s23, 0
	s_mov_b32 m0, s53
	ds_read_b128 v[174:177], v140 offset:32768
	ds_read_b128 v[178:181], v140 offset:33792
	ds_read_b128 v[182:185], v140 offset:34816
	ds_read_b128 v[186:189], v140 offset:35840
	ds_read_b128 v[190:193], v140 offset:36864
	ds_read_b128 v[194:197], v140 offset:37888
	ds_read_b128 v[198:201], v140 offset:38912
	ds_read_b128 v[202:205], v140 offset:39936
	global_load_lds_dwordx4 v208, s[22:23]
	s_mov_b32 m0, s85
	s_nop 0
	global_load_lds_dwordx4 v128, s[22:23]
	s_waitcnt vmcnt(8)
	s_waitcnt lgkmcnt(0)
	s_barrier
	v_mfma_f32_16x16x32_bf16 v[124:127], v[142:145], v[174:177], v[124:127]
	v_mfma_f32_16x16x32_bf16 v[120:123], v[150:153], v[174:177], v[120:123]
	v_mfma_f32_16x16x32_bf16 v[108:111], v[142:145], v[182:185], v[108:111]
	v_mfma_f32_16x16x32_bf16 v[104:107], v[150:153], v[182:185], v[104:107]
	v_mfma_f32_16x16x32_bf16 v[92:95], v[142:145], v[190:193], v[92:95]
	v_mfma_f32_16x16x32_bf16 v[88:91], v[150:153], v[190:193], v[88:91]
	v_mfma_f32_16x16x32_bf16 v[76:79], v[142:145], v[198:201], v[76:79]
	v_mfma_f32_16x16x32_bf16 v[72:75], v[150:153], v[198:201], v[72:75]
	v_mfma_f32_16x16x32_bf16 v[124:127], v[146:149], v[178:181], v[124:127]
	v_mfma_f32_16x16x32_bf16 v[120:123], v[154:157], v[178:181], v[120:123]
	v_mfma_f32_16x16x32_bf16 v[108:111], v[146:149], v[186:189], v[108:111]
	v_mfma_f32_16x16x32_bf16 v[104:107], v[154:157], v[186:189], v[104:107]
	v_mfma_f32_16x16x32_bf16 v[92:95], v[146:149], v[194:197], v[92:95]
	v_mfma_f32_16x16x32_bf16 v[88:91], v[154:157], v[194:197], v[88:91]
	v_mfma_f32_16x16x32_bf16 v[76:79], v[146:149], v[202:205], v[76:79]
	v_mfma_f32_16x16x32_bf16 v[72:75], v[154:157], v[202:205], v[72:75]
	v_mfma_f32_16x16x32_bf16 v[116:119], v[158:161], v[174:177], v[116:119]
	v_mfma_f32_16x16x32_bf16 v[112:115], v[166:169], v[174:177], v[112:115]
	v_mfma_f32_16x16x32_bf16 v[100:103], v[158:161], v[182:185], v[100:103]
	v_mfma_f32_16x16x32_bf16 v[96:99], v[166:169], v[182:185], v[96:99]
	v_mfma_f32_16x16x32_bf16 v[84:87], v[158:161], v[190:193], v[84:87]
	v_mfma_f32_16x16x32_bf16 v[80:83], v[166:169], v[190:193], v[80:83]
	v_mfma_f32_16x16x32_bf16 v[68:71], v[158:161], v[198:201], v[68:71]
	v_mfma_f32_16x16x32_bf16 v[64:67], v[166:169], v[198:201], v[64:67]
	v_mfma_f32_16x16x32_bf16 v[116:119], v[162:165], v[178:181], v[116:119]
	v_mfma_f32_16x16x32_bf16 v[112:115], v[170:173], v[178:181], v[112:115]
	v_mfma_f32_16x16x32_bf16 v[100:103], v[162:165], v[186:189], v[100:103]
	v_mfma_f32_16x16x32_bf16 v[96:99], v[170:173], v[186:189], v[96:99]
	v_mfma_f32_16x16x32_bf16 v[84:87], v[162:165], v[194:197], v[84:87]
	v_mfma_f32_16x16x32_bf16 v[80:83], v[170:173], v[194:197], v[80:83]
	v_mfma_f32_16x16x32_bf16 v[68:71], v[162:165], v[202:205], v[68:71]
	v_mfma_f32_16x16x32_bf16 v[64:67], v[170:173], v[202:205], v[64:67]
	s_barrier
	s_add_i32 s22, s80, s43
	s_add_i32 m0, s22, 0xffffff80
	ds_read_b128 v[174:177], v140 offset:49152
	ds_read_b128 v[178:181], v140 offset:50176
	ds_read_b128 v[182:185], v140 offset:51200
	ds_read_b128 v[186:189], v140 offset:52224
	ds_read_b128 v[190:193], v140 offset:53248
	ds_read_b128 v[194:197], v140 offset:54272
	ds_read_b128 v[198:201], v140 offset:55296
	ds_read_b128 v[202:205], v140 offset:56320
	global_load_lds_dwordx4 v208, vcc offset:128
	s_add_i32 m0, s22, 0x1f80
	s_add_u32 s22, vcc_lo, 0x80080
	s_addc_u32 s23, vcc_hi, 0
	s_add_i32 s80, s81, s43
	global_load_lds_dwordx4 v128, vcc offset:128
	s_mov_b32 m0, s80
	s_nop 0
	global_load_lds_dwordx4 v208, s[22:23]
	s_add_i32 m0, s80, 0x2000
	s_nop 0
	global_load_lds_dwordx4 v128, s[22:23]
	s_add_u32 s22, s92, s76
	s_addc_u32 s23, s93, s77
	s_cmp_eq_u32 s44, 0
	s_cselect_b32 s23, s15, s23
	s_cselect_b32 s22, s91, s22
	s_add_i32 m0, s9, 0xffffff80
	s_nop 0
	global_load_lds_dwordx4 v208, s[22:23] offset:128
	s_add_i32 m0, s12, 0xffffff80
	s_nop 0
	global_load_lds_dwordx4 v128, s[22:23] offset:128
	s_waitcnt vmcnt(8)
	s_waitcnt lgkmcnt(0)
	s_barrier
	v_mfma_f32_16x16x32_bf16 v[60:63], v[142:145], v[174:177], v[60:63]
	v_mfma_f32_16x16x32_bf16 v[56:59], v[150:153], v[174:177], v[56:59]
	v_mfma_f32_16x16x32_bf16 v[44:47], v[142:145], v[182:185], v[44:47]
	v_mfma_f32_16x16x32_bf16 v[40:43], v[150:153], v[182:185], v[40:43]
	v_mfma_f32_16x16x32_bf16 v[28:31], v[142:145], v[190:193], v[28:31]
	v_mfma_f32_16x16x32_bf16 v[24:27], v[150:153], v[190:193], v[24:27]
	v_mfma_f32_16x16x32_bf16 v[12:15], v[142:145], v[198:201], v[12:15]
	v_mfma_f32_16x16x32_bf16 v[8:11], v[150:153], v[198:201], v[8:11]
	v_mfma_f32_16x16x32_bf16 v[60:63], v[146:149], v[178:181], v[60:63]
	v_mfma_f32_16x16x32_bf16 v[56:59], v[154:157], v[178:181], v[56:59]
	v_mfma_f32_16x16x32_bf16 v[44:47], v[146:149], v[186:189], v[44:47]
	v_mfma_f32_16x16x32_bf16 v[40:43], v[154:157], v[186:189], v[40:43]
	v_mfma_f32_16x16x32_bf16 v[28:31], v[146:149], v[194:197], v[28:31]
	v_mfma_f32_16x16x32_bf16 v[24:27], v[154:157], v[194:197], v[24:27]
	v_mfma_f32_16x16x32_bf16 v[12:15], v[146:149], v[202:205], v[12:15]
	v_mfma_f32_16x16x32_bf16 v[8:11], v[154:157], v[202:205], v[8:11]
	v_mfma_f32_16x16x32_bf16 v[52:55], v[158:161], v[174:177], v[52:55]
	v_mfma_f32_16x16x32_bf16 v[48:51], v[166:169], v[174:177], v[48:51]
	v_mfma_f32_16x16x32_bf16 v[36:39], v[158:161], v[182:185], v[36:39]
	v_mfma_f32_16x16x32_bf16 v[32:35], v[166:169], v[182:185], v[32:35]
	v_mfma_f32_16x16x32_bf16 v[20:23], v[158:161], v[190:193], v[20:23]
	v_mfma_f32_16x16x32_bf16 v[16:19], v[166:169], v[190:193], v[16:19]
	v_mfma_f32_16x16x32_bf16 v[4:7], v[158:161], v[198:201], v[4:7]
	v_mfma_f32_16x16x32_bf16 v[0:3], v[166:169], v[198:201], v[0:3]
	v_mfma_f32_16x16x32_bf16 v[52:55], v[162:165], v[178:181], v[52:55]
	v_mfma_f32_16x16x32_bf16 v[48:51], v[170:173], v[178:181], v[48:51]
	v_mfma_f32_16x16x32_bf16 v[36:39], v[162:165], v[186:189], v[36:39]
	v_mfma_f32_16x16x32_bf16 v[32:35], v[170:173], v[186:189], v[32:35]
	v_mfma_f32_16x16x32_bf16 v[20:23], v[162:165], v[194:197], v[20:23]
	v_mfma_f32_16x16x32_bf16 v[16:19], v[170:173], v[194:197], v[16:19]
	v_mfma_f32_16x16x32_bf16 v[4:7], v[162:165], v[202:205], v[4:7]
	v_mfma_f32_16x16x32_bf16 v[0:3], v[170:173], v[202:205], v[0:3]
	s_barrier
	s_addk_i32 s44, 0x200
	s_add_u32 s76, s76, 0x100
	s_addc_u32 s77, s77, 0
	s_add_i32 s22, s82, 2
	v_lshl_add_u64 v[136:137], v[136:137], 0, s[58:59]
	s_cmp_gt_u32 s82, 29
	v_lshl_add_u64 v[134:135], v[134:135], 0, s[58:59]
	s_cbranch_scc1 .LBB0_1261
	s_mov_b32 s82, s22
	s_branch .LBB0_1257
